# two-group GEMM start stagger with half-period delays: 5 sleeps in the QKV phase, 4 in the up-projection phase
# speedup vs baseline: 1.0078x; 1.0078x over previous
; __global__ void __launch_bounds__(NWAVES * 64, 2) hymba_fwd(Args A) {
;     ...
;     {
;         pg8::Gemm g{(const pg8::bf16_t*)(ws + WS_XA), (const pg8::bf16_t*)(ws + WS_W1), M1, DIN, DM, DM};
;         pg8::StaticOrder S; S.init(M1, DIN, G, bx);
;         pg8::Epi1 E{(const float*)(ws + WS_RS1), (const float*)(ws + WS_ROPE), A.out, (pg8::bf16_t*)(ws + WS_QD), (pg8::bf16_t*)(ws + WS_QS), (pg8::bf16_t*)(ws + WS_KD), (pg8::bf16_t*)(ws + WS_KS),
;                     (pg8::bf16_t*)(ws + WS_VDT), (pg8::bf16_t*)(ws + WS_VST)};
;         pg8::gemm_phase<pg8::Epi1, pg8::StaticOrder, true, true>(lds, g, S, E);
.LBB0_102:
	s_or_b64 exec, exec, s[0:1]
	s_barrier
	s_cmp_lt_u32 s22, 36
	s_cbranch_scc1 .Lstag_p1
	s_bitcmp1_b32 s22, 3
	s_cbranch_scc0 .Lstag_p1
	s_sleep 127
	s_sleep 127
	s_sleep 127
	s_sleep 127
	s_sleep 127

; __global__ void __launch_bounds__(NWAVES * 64, 2) hymba_fwd(Args A) {
;     ...
;     xcd_barrier(bar);
;     {
;         pg8::Gemm g{(const pg8::bf16_t*)(ws + WS_X1B), (const pg8::bf16_t*)(ws + WS_W3), M2, DFF, DM, DM};
;         pg8::StaticOrder S; S.init(M2, DFF, G, bx);
;         pg8::Epi3 E{(const float*)(ws + WS_SS2), (pg8::bf16_t*)(ws + WS_H)};
;         pg8::gemm_phase<pg8::Epi3, pg8::StaticOrder, true, true>(lds, g, S, E);
.LBB0_746:
	s_or_b64 exec, exec, s[0:1]
	v_mov_b32_e32 v9, v138
	s_waitcnt lgkmcnt(0)
	s_barrier
	s_cmp_lt_u32 s22, 32
	s_cbranch_scc1 .Lstag_p4
	s_bitcmp1_b32 s22, 3
	s_cbranch_scc0 .Lstag_p4
	s_sleep 127
	s_sleep 127
	s_sleep 127
	s_sleep 127
